# LRU GEMM epilogue (plain and gelu halves) as a contiguous fast path with dwordx4 stores
# speedup vs baseline: 1.0163x; 1.0027x over previous
.Lgate_no:
	s_cmp_lg_u32 s79, 20
	s_cbranch_scc1 .Llru_no
	v_lshlrev_b64 v[244:245], 11, v[138:139]
	v_lshl_add_u64 v[244:245], s[48:49], 0, v[244:245]
	v_mbcnt_lo_u32_b32 v246, -1, 0
	v_mbcnt_hi_u32_b32 v246, -1, v246
	v_and_b32_e32 v246, 16, v246
	v_lshrrev_b32_e32 v247, 1, v246
	v_add_u32_e32 v246, v246, v247
	v_and_b32_e32 v247, 0x3ff, v136
	v_lshl_add_u32 v246, v247, 1, v246
	v_mov_b32_e32 v247, 0
	v_lshl_add_u64 v[244:245], v[246:247], 0, v[244:245]
	s_ashr_i32 s2, s67, 2
	s_add_i32 s2, s2, 2
	s_mul_i32 s2, s2, 0x2100000
	s_mov_b32 s3, 0
	v_lshl_add_u64 v[244:245], v[244:245], 0, s[2:3]
	s_cmpk_lt_u32 s27, 0x400
	s_cbranch_scc1 .Llru_plain
	v_mul_f32_e32 v194, 0x3d372713, v124
	v_mul_f32_e32 v195, 0x3d372713, v125
	v_mul_f32_e32 v196, 0x3d372713, v126
	v_mul_f32_e32 v197, 0x3d372713, v127
	v_mul_f32_e32 v198, 0x3d372713, v120
	v_mul_f32_e32 v199, 0x3d372713, v121
	v_mul_f32_e32 v200, 0x3d372713, v122
	v_mul_f32_e32 v201, 0x3d372713, v123
	v_mul_f32_e32 v194, v124, v194
	v_mul_f32_e32 v195, v125, v195
	v_mul_f32_e32 v196, v126, v196
	v_mul_f32_e32 v197, v127, v197
	v_mul_f32_e32 v198, v120, v198
	v_mul_f32_e32 v199, v121, v199
	v_mul_f32_e32 v200, v122, v200
	v_mul_f32_e32 v201, v123, v201
	v_fma_f32 v194, v124, v194, v124
	v_fma_f32 v195, v125, v195, v125
	v_fma_f32 v196, v126, v196, v126
	v_fma_f32 v197, v127, v197, v127
	v_fma_f32 v198, v120, v198, v120
	v_fma_f32 v199, v121, v199, v121
	v_fma_f32 v200, v122, v200, v122
	v_fma_f32 v201, v123, v201, v123
	v_mul_f32_e32 v194, 0x3f4c422a, v194
	v_mul_f32_e32 v195, 0x3f4c422a, v195
	v_mul_f32_e32 v196, 0x3f4c422a, v196
	v_mul_f32_e32 v197, 0x3f4c422a, v197
	v_mul_f32_e32 v198, 0x3f4c422a, v198
	v_mul_f32_e32 v199, 0x3f4c422a, v199
	v_mul_f32_e32 v200, 0x3f4c422a, v200
	v_mul_f32_e32 v201, 0x3f4c422a, v201
	v_add_f32_e32 v194, v194, v194
	v_add_f32_e32 v195, v195, v195
	v_add_f32_e32 v196, v196, v196
	v_add_f32_e32 v197, v197, v197
	v_add_f32_e32 v198, v198, v198
	v_add_f32_e32 v199, v199, v199
	v_add_f32_e32 v200, v200, v200
	v_add_f32_e32 v201, v201, v201
	v_mul_f32_e32 v194, 0xbfb8aa3b, v194
	v_mul_f32_e32 v195, 0xbfb8aa3b, v195
	v_mul_f32_e32 v196, 0xbfb8aa3b, v196
	v_mul_f32_e32 v197, 0xbfb8aa3b, v197
	v_mul_f32_e32 v198, 0xbfb8aa3b, v198
	v_mul_f32_e32 v199, 0xbfb8aa3b, v199
	v_mul_f32_e32 v200, 0xbfb8aa3b, v200
	v_mul_f32_e32 v201, 0xbfb8aa3b, v201
	v_exp_f32_e32 v194, v194
	v_exp_f32_e32 v195, v195
	v_exp_f32_e32 v196, v196
	v_exp_f32_e32 v197, v197
	v_exp_f32_e32 v198, v198
	v_exp_f32_e32 v199, v199
	v_exp_f32_e32 v200, v200
	v_exp_f32_e32 v201, v201
	v_add_f32_e32 v194, 1.0, v194
	v_add_f32_e32 v195, 1.0, v195
	v_add_f32_e32 v196, 1.0, v196
	v_add_f32_e32 v197, 1.0, v197
	v_add_f32_e32 v198, 1.0, v198
	v_add_f32_e32 v199, 1.0, v199
	v_add_f32_e32 v200, 1.0, v200
	v_add_f32_e32 v201, 1.0, v201
	v_rcp_f32_e32 v194, v194
	v_rcp_f32_e32 v195, v195
	v_rcp_f32_e32 v196, v196
	v_rcp_f32_e32 v197, v197
	v_rcp_f32_e32 v198, v198
	v_rcp_f32_e32 v199, v199
	v_rcp_f32_e32 v200, v200
	v_rcp_f32_e32 v201, v201
	v_mul_f32_e32 v124, v124, v194
	v_mul_f32_e32 v125, v125, v195
	v_mul_f32_e32 v126, v126, v196
	v_mul_f32_e32 v127, v127, v197
	v_mul_f32_e32 v120, v120, v198
	v_mul_f32_e32 v121, v121, v199
	v_mul_f32_e32 v122, v122, v200
	v_mul_f32_e32 v123, v123, v201
	v_cvt_pk_bf16_f32 v230, v124, v125
	v_cvt_pk_bf16_f32 v231, v126, v127
	v_cvt_pk_bf16_f32 v232, v120, v121
	v_cvt_pk_bf16_f32 v233, v122, v123
	s_nop 1
	v_permlane16_swap_b32 v230, v232
	v_permlane16_swap_b32 v231, v233
	global_store_dwordx4 v[244:245], v[230:233], off
	v_mul_f32_e32 v194, 0x3d372713, v116
	v_mul_f32_e32 v195, 0x3d372713, v117
	v_mul_f32_e32 v196, 0x3d372713, v118
	v_mul_f32_e32 v197, 0x3d372713, v119
	v_mul_f32_e32 v198, 0x3d372713, v112
	v_mul_f32_e32 v199, 0x3d372713, v113
	v_mul_f32_e32 v200, 0x3d372713, v114
	v_mul_f32_e32 v201, 0x3d372713, v115
	v_mul_f32_e32 v194, v116, v194
	v_mul_f32_e32 v195, v117, v195
	v_mul_f32_e32 v196, v118, v196
	v_mul_f32_e32 v197, v119, v197
	v_mul_f32_e32 v198, v112, v198
	v_mul_f32_e32 v199, v113, v199
	v_mul_f32_e32 v200, v114, v200
	v_mul_f32_e32 v201, v115, v201
	v_fma_f32 v194, v116, v194, v116
	v_fma_f32 v195, v117, v195, v117
	v_fma_f32 v196, v118, v196, v118
	v_fma_f32 v197, v119, v197, v119
	v_fma_f32 v198, v112, v198, v112
	v_fma_f32 v199, v113, v199, v113
	v_fma_f32 v200, v114, v200, v114
	v_fma_f32 v201, v115, v201, v115
	v_mul_f32_e32 v194, 0x3f4c422a, v194
	v_mul_f32_e32 v195, 0x3f4c422a, v195
	v_mul_f32_e32 v196, 0x3f4c422a, v196
	v_mul_f32_e32 v197, 0x3f4c422a, v197
	v_mul_f32_e32 v198, 0x3f4c422a, v198
	v_mul_f32_e32 v199, 0x3f4c422a, v199
	v_mul_f32_e32 v200, 0x3f4c422a, v200
	v_mul_f32_e32 v201, 0x3f4c422a, v201
	v_add_f32_e32 v194, v194, v194
	v_add_f32_e32 v195, v195, v195
	v_add_f32_e32 v196, v196, v196
	v_add_f32_e32 v197, v197, v197
	v_add_f32_e32 v198, v198, v198
	v_add_f32_e32 v199, v199, v199
	v_add_f32_e32 v200, v200, v200
	v_add_f32_e32 v201, v201, v201
	v_mul_f32_e32 v194, 0xbfb8aa3b, v194
	v_mul_f32_e32 v195, 0xbfb8aa3b, v195
	v_mul_f32_e32 v196, 0xbfb8aa3b, v196
	v_mul_f32_e32 v197, 0xbfb8aa3b, v197
	v_mul_f32_e32 v198, 0xbfb8aa3b, v198
	v_mul_f32_e32 v199, 0xbfb8aa3b, v199
	v_mul_f32_e32 v200, 0xbfb8aa3b, v200
	v_mul_f32_e32 v201, 0xbfb8aa3b, v201
	v_exp_f32_e32 v194, v194
	v_exp_f32_e32 v195, v195
	v_exp_f32_e32 v196, v196
	v_exp_f32_e32 v197, v197
	v_exp_f32_e32 v198, v198
	v_exp_f32_e32 v199, v199
	v_exp_f32_e32 v200, v200
	v_exp_f32_e32 v201, v201
	v_add_f32_e32 v194, 1.0, v194
	v_add_f32_e32 v195, 1.0, v195
	v_add_f32_e32 v196, 1.0, v196
	v_add_f32_e32 v197, 1.0, v197
	v_add_f32_e32 v198, 1.0, v198
	v_add_f32_e32 v199, 1.0, v199
	v_add_f32_e32 v200, 1.0, v200
	v_add_f32_e32 v201, 1.0, v201
	v_rcp_f32_e32 v194, v194
	v_rcp_f32_e32 v195, v195
	v_rcp_f32_e32 v196, v196
	v_rcp_f32_e32 v197, v197
	v_rcp_f32_e32 v198, v198
	v_rcp_f32_e32 v199, v199
	v_rcp_f32_e32 v200, v200
	v_rcp_f32_e32 v201, v201
	v_mul_f32_e32 v116, v116, v194
	v_mul_f32_e32 v117, v117, v195
	v_mul_f32_e32 v118, v118, v196
	v_mul_f32_e32 v119, v119, v197
	v_mul_f32_e32 v112, v112, v198
	v_mul_f32_e32 v113, v113, v199
	v_mul_f32_e32 v114, v114, v200
	v_mul_f32_e32 v115, v115, v201
	v_cvt_pk_bf16_f32 v234, v116, v117
	v_cvt_pk_bf16_f32 v235, v118, v119
	v_cvt_pk_bf16_f32 v236, v112, v113
	v_cvt_pk_bf16_f32 v237, v114, v115
	v_add_co_u32_e32 v246, vcc, 0x100, v244
	v_addc_co_u32_e32 v247, vcc, 0, v245, vcc
	v_permlane16_swap_b32 v234, v236
	v_permlane16_swap_b32 v235, v237
	global_store_dwordx4 v[246:247], v[234:237], off
	v_mul_f32_e32 v194, 0x3d372713, v108
	v_mul_f32_e32 v195, 0x3d372713, v109
	v_mul_f32_e32 v196, 0x3d372713, v110
	v_mul_f32_e32 v197, 0x3d372713, v111
	v_mul_f32_e32 v198, 0x3d372713, v104
	v_mul_f32_e32 v199, 0x3d372713, v105
	v_mul_f32_e32 v200, 0x3d372713, v106
	v_mul_f32_e32 v201, 0x3d372713, v107
	v_mul_f32_e32 v194, v108, v194
	v_mul_f32_e32 v195, v109, v195
	v_mul_f32_e32 v196, v110, v196
	v_mul_f32_e32 v197, v111, v197
	v_mul_f32_e32 v198, v104, v198
	v_mul_f32_e32 v199, v105, v199
	v_mul_f32_e32 v200, v106, v200
	v_mul_f32_e32 v201, v107, v201
	v_fma_f32 v194, v108, v194, v108
	v_fma_f32 v195, v109, v195, v109
	v_fma_f32 v196, v110, v196, v110
	v_fma_f32 v197, v111, v197, v111
	v_fma_f32 v198, v104, v198, v104
	v_fma_f32 v199, v105, v199, v105
	v_fma_f32 v200, v106, v200, v106
	v_fma_f32 v201, v107, v201, v107
	v_mul_f32_e32 v194, 0x3f4c422a, v194
	v_mul_f32_e32 v195, 0x3f4c422a, v195
	v_mul_f32_e32 v196, 0x3f4c422a, v196
	v_mul_f32_e32 v197, 0x3f4c422a, v197
	v_mul_f32_e32 v198, 0x3f4c422a, v198
	v_mul_f32_e32 v199, 0x3f4c422a, v199
	v_mul_f32_e32 v200, 0x3f4c422a, v200
	v_mul_f32_e32 v201, 0x3f4c422a, v201
	v_add_f32_e32 v194, v194, v194
	v_add_f32_e32 v195, v195, v195
	v_add_f32_e32 v196, v196, v196
	v_add_f32_e32 v197, v197, v197
	v_add_f32_e32 v198, v198, v198
	v_add_f32_e32 v199, v199, v199
	v_add_f32_e32 v200, v200, v200
	v_add_f32_e32 v201, v201, v201
	v_mul_f32_e32 v194, 0xbfb8aa3b, v194
	v_mul_f32_e32 v195, 0xbfb8aa3b, v195
	v_mul_f32_e32 v196, 0xbfb8aa3b, v196
	v_mul_f32_e32 v197, 0xbfb8aa3b, v197
	v_mul_f32_e32 v198, 0xbfb8aa3b, v198
	v_mul_f32_e32 v199, 0xbfb8aa3b, v199
	v_mul_f32_e32 v200, 0xbfb8aa3b, v200
	v_mul_f32_e32 v201, 0xbfb8aa3b, v201
	v_exp_f32_e32 v194, v194
	v_exp_f32_e32 v195, v195
	v_exp_f32_e32 v196, v196
	v_exp_f32_e32 v197, v197
	v_exp_f32_e32 v198, v198
	v_exp_f32_e32 v199, v199
	v_exp_f32_e32 v200, v200
	v_exp_f32_e32 v201, v201
	v_add_f32_e32 v194, 1.0, v194
	v_add_f32_e32 v195, 1.0, v195
	v_add_f32_e32 v196, 1.0, v196
	v_add_f32_e32 v197, 1.0, v197
	v_add_f32_e32 v198, 1.0, v198
	v_add_f32_e32 v199, 1.0, v199
	v_add_f32_e32 v200, 1.0, v200
	v_add_f32_e32 v201, 1.0, v201
	v_rcp_f32_e32 v194, v194
	v_rcp_f32_e32 v195, v195
	v_rcp_f32_e32 v196, v196
	v_rcp_f32_e32 v197, v197
	v_rcp_f32_e32 v198, v198
	v_rcp_f32_e32 v199, v199
	v_rcp_f32_e32 v200, v200
	v_rcp_f32_e32 v201, v201
	v_mul_f32_e32 v108, v108, v194
	v_mul_f32_e32 v109, v109, v195
	v_mul_f32_e32 v110, v110, v196
	v_mul_f32_e32 v111, v111, v197
	v_mul_f32_e32 v104, v104, v198
	v_mul_f32_e32 v105, v105, v199
	v_mul_f32_e32 v106, v106, v200
	v_mul_f32_e32 v107, v107, v201
	v_cvt_pk_bf16_f32 v230, v108, v109
	v_cvt_pk_bf16_f32 v231, v110, v111
	v_cvt_pk_bf16_f32 v232, v104, v105
	v_cvt_pk_bf16_f32 v233, v106, v107
	v_add_co_u32_e32 v246, vcc, 0x8000, v244
	v_addc_co_u32_e32 v247, vcc, 0, v245, vcc
	v_permlane16_swap_b32 v230, v232
	v_permlane16_swap_b32 v231, v233
	global_store_dwordx4 v[246:247], v[230:233], off
	v_mul_f32_e32 v194, 0x3d372713, v100
	v_mul_f32_e32 v195, 0x3d372713, v101
	v_mul_f32_e32 v196, 0x3d372713, v102
	v_mul_f32_e32 v197, 0x3d372713, v103
	v_mul_f32_e32 v198, 0x3d372713, v96
	v_mul_f32_e32 v199, 0x3d372713, v97
	v_mul_f32_e32 v200, 0x3d372713, v98
	v_mul_f32_e32 v201, 0x3d372713, v99
	v_mul_f32_e32 v194, v100, v194
	v_mul_f32_e32 v195, v101, v195
	v_mul_f32_e32 v196, v102, v196
	v_mul_f32_e32 v197, v103, v197
	v_mul_f32_e32 v198, v96, v198
	v_mul_f32_e32 v199, v97, v199
	v_mul_f32_e32 v200, v98, v200
	v_mul_f32_e32 v201, v99, v201
	v_fma_f32 v194, v100, v194, v100
	v_fma_f32 v195, v101, v195, v101
	v_fma_f32 v196, v102, v196, v102
	v_fma_f32 v197, v103, v197, v103
	v_fma_f32 v198, v96, v198, v96
	v_fma_f32 v199, v97, v199, v97
	v_fma_f32 v200, v98, v200, v98
	v_fma_f32 v201, v99, v201, v99
	v_mul_f32_e32 v194, 0x3f4c422a, v194
	v_mul_f32_e32 v195, 0x3f4c422a, v195
	v_mul_f32_e32 v196, 0x3f4c422a, v196
	v_mul_f32_e32 v197, 0x3f4c422a, v197
	v_mul_f32_e32 v198, 0x3f4c422a, v198
	v_mul_f32_e32 v199, 0x3f4c422a, v199
	v_mul_f32_e32 v200, 0x3f4c422a, v200
	v_mul_f32_e32 v201, 0x3f4c422a, v201
	v_add_f32_e32 v194, v194, v194
	v_add_f32_e32 v195, v195, v195
	v_add_f32_e32 v196, v196, v196
	v_add_f32_e32 v197, v197, v197
	v_add_f32_e32 v198, v198, v198
	v_add_f32_e32 v199, v199, v199
	v_add_f32_e32 v200, v200, v200
	v_add_f32_e32 v201, v201, v201
	v_mul_f32_e32 v194, 0xbfb8aa3b, v194
	v_mul_f32_e32 v195, 0xbfb8aa3b, v195
	v_mul_f32_e32 v196, 0xbfb8aa3b, v196
	v_mul_f32_e32 v197, 0xbfb8aa3b, v197
	v_mul_f32_e32 v198, 0xbfb8aa3b, v198
	v_mul_f32_e32 v199, 0xbfb8aa3b, v199
	v_mul_f32_e32 v200, 0xbfb8aa3b, v200
	v_mul_f32_e32 v201, 0xbfb8aa3b, v201
	v_exp_f32_e32 v194, v194
	v_exp_f32_e32 v195, v195
	v_exp_f32_e32 v196, v196
	v_exp_f32_e32 v197, v197
	v_exp_f32_e32 v198, v198
	v_exp_f32_e32 v199, v199
	v_exp_f32_e32 v200, v200
	v_exp_f32_e32 v201, v201
	v_add_f32_e32 v194, 1.0, v194
	v_add_f32_e32 v195, 1.0, v195
	v_add_f32_e32 v196, 1.0, v196
	v_add_f32_e32 v197, 1.0, v197
	v_add_f32_e32 v198, 1.0, v198
	v_add_f32_e32 v199, 1.0, v199
	v_add_f32_e32 v200, 1.0, v200
	v_add_f32_e32 v201, 1.0, v201
	v_rcp_f32_e32 v194, v194
	v_rcp_f32_e32 v195, v195
	v_rcp_f32_e32 v196, v196
	v_rcp_f32_e32 v197, v197
	v_rcp_f32_e32 v198, v198
	v_rcp_f32_e32 v199, v199
	v_rcp_f32_e32 v200, v200
	v_rcp_f32_e32 v201, v201
	v_mul_f32_e32 v100, v100, v194
	v_mul_f32_e32 v101, v101, v195
	v_mul_f32_e32 v102, v102, v196
	v_mul_f32_e32 v103, v103, v197
	v_mul_f32_e32 v96, v96, v198
	v_mul_f32_e32 v97, v97, v199
	v_mul_f32_e32 v98, v98, v200
	v_mul_f32_e32 v99, v99, v201
	v_cvt_pk_bf16_f32 v234, v100, v101
	v_cvt_pk_bf16_f32 v235, v102, v103
	v_cvt_pk_bf16_f32 v236, v96, v97
	v_cvt_pk_bf16_f32 v237, v98, v99
	v_add_co_u32_e32 v246, vcc, 0x8100, v244
	v_addc_co_u32_e32 v247, vcc, 0, v245, vcc
	v_permlane16_swap_b32 v234, v236
	v_permlane16_swap_b32 v235, v237
	global_store_dwordx4 v[246:247], v[234:237], off
	v_mul_f32_e32 v194, 0x3d372713, v92
	v_mul_f32_e32 v195, 0x3d372713, v93
	v_mul_f32_e32 v196, 0x3d372713, v94
	v_mul_f32_e32 v197, 0x3d372713, v95
	v_mul_f32_e32 v198, 0x3d372713, v88
	v_mul_f32_e32 v199, 0x3d372713, v89
	v_mul_f32_e32 v200, 0x3d372713, v90
	v_mul_f32_e32 v201, 0x3d372713, v91
	v_mul_f32_e32 v194, v92, v194
	v_mul_f32_e32 v195, v93, v195
	v_mul_f32_e32 v196, v94, v196
	v_mul_f32_e32 v197, v95, v197
	v_mul_f32_e32 v198, v88, v198
	v_mul_f32_e32 v199, v89, v199
	v_mul_f32_e32 v200, v90, v200
	v_mul_f32_e32 v201, v91, v201
	v_fma_f32 v194, v92, v194, v92
	v_fma_f32 v195, v93, v195, v93
	v_fma_f32 v196, v94, v196, v94
	v_fma_f32 v197, v95, v197, v95
	v_fma_f32 v198, v88, v198, v88
	v_fma_f32 v199, v89, v199, v89
	v_fma_f32 v200, v90, v200, v90
	v_fma_f32 v201, v91, v201, v91
	v_mul_f32_e32 v194, 0x3f4c422a, v194
	v_mul_f32_e32 v195, 0x3f4c422a, v195
	v_mul_f32_e32 v196, 0x3f4c422a, v196
	v_mul_f32_e32 v197, 0x3f4c422a, v197
	v_mul_f32_e32 v198, 0x3f4c422a, v198
	v_mul_f32_e32 v199, 0x3f4c422a, v199
	v_mul_f32_e32 v200, 0x3f4c422a, v200
	v_mul_f32_e32 v201, 0x3f4c422a, v201
	v_add_f32_e32 v194, v194, v194
	v_add_f32_e32 v195, v195, v195
	v_add_f32_e32 v196, v196, v196
	v_add_f32_e32 v197, v197, v197
	v_add_f32_e32 v198, v198, v198
	v_add_f32_e32 v199, v199, v199
	v_add_f32_e32 v200, v200, v200
	v_add_f32_e32 v201, v201, v201
	v_mul_f32_e32 v194, 0xbfb8aa3b, v194
	v_mul_f32_e32 v195, 0xbfb8aa3b, v195
	v_mul_f32_e32 v196, 0xbfb8aa3b, v196
	v_mul_f32_e32 v197, 0xbfb8aa3b, v197
	v_mul_f32_e32 v198, 0xbfb8aa3b, v198
	v_mul_f32_e32 v199, 0xbfb8aa3b, v199
	v_mul_f32_e32 v200, 0xbfb8aa3b, v200
	v_mul_f32_e32 v201, 0xbfb8aa3b, v201
	v_exp_f32_e32 v194, v194
	v_exp_f32_e32 v195, v195
	v_exp_f32_e32 v196, v196
	v_exp_f32_e32 v197, v197
	v_exp_f32_e32 v198, v198
	v_exp_f32_e32 v199, v199
	v_exp_f32_e32 v200, v200
	v_exp_f32_e32 v201, v201
	v_add_f32_e32 v194, 1.0, v194
	v_add_f32_e32 v195, 1.0, v195
	v_add_f32_e32 v196, 1.0, v196
	v_add_f32_e32 v197, 1.0, v197
	v_add_f32_e32 v198, 1.0, v198
	v_add_f32_e32 v199, 1.0, v199
	v_add_f32_e32 v200, 1.0, v200
	v_add_f32_e32 v201, 1.0, v201
	v_rcp_f32_e32 v194, v194
	v_rcp_f32_e32 v195, v195
	v_rcp_f32_e32 v196, v196
	v_rcp_f32_e32 v197, v197
	v_rcp_f32_e32 v198, v198
	v_rcp_f32_e32 v199, v199
	v_rcp_f32_e32 v200, v200
	v_rcp_f32_e32 v201, v201
	v_mul_f32_e32 v92, v92, v194
	v_mul_f32_e32 v93, v93, v195
	v_mul_f32_e32 v94, v94, v196
	v_mul_f32_e32 v95, v95, v197
	v_mul_f32_e32 v88, v88, v198
	v_mul_f32_e32 v89, v89, v199
	v_mul_f32_e32 v90, v90, v200
	v_mul_f32_e32 v91, v91, v201
	v_cvt_pk_bf16_f32 v230, v92, v93
	v_cvt_pk_bf16_f32 v231, v94, v95
	v_cvt_pk_bf16_f32 v232, v88, v89
	v_cvt_pk_bf16_f32 v233, v90, v91
	v_add_co_u32_e32 v246, vcc, 0x10000, v244
	v_addc_co_u32_e32 v247, vcc, 0, v245, vcc
	v_permlane16_swap_b32 v230, v232
	v_permlane16_swap_b32 v231, v233
	global_store_dwordx4 v[246:247], v[230:233], off
	v_mul_f32_e32 v194, 0x3d372713, v84
	v_mul_f32_e32 v195, 0x3d372713, v85
	v_mul_f32_e32 v196, 0x3d372713, v86
	v_mul_f32_e32 v197, 0x3d372713, v87
	v_mul_f32_e32 v198, 0x3d372713, v80
	v_mul_f32_e32 v199, 0x3d372713, v81
	v_mul_f32_e32 v200, 0x3d372713, v82
	v_mul_f32_e32 v201, 0x3d372713, v83
	v_mul_f32_e32 v194, v84, v194
	v_mul_f32_e32 v195, v85, v195
	v_mul_f32_e32 v196, v86, v196
	v_mul_f32_e32 v197, v87, v197
	v_mul_f32_e32 v198, v80, v198
	v_mul_f32_e32 v199, v81, v199
	v_mul_f32_e32 v200, v82, v200
	v_mul_f32_e32 v201, v83, v201
	v_fma_f32 v194, v84, v194, v84
	v_fma_f32 v195, v85, v195, v85
	v_fma_f32 v196, v86, v196, v86
	v_fma_f32 v197, v87, v197, v87
	v_fma_f32 v198, v80, v198, v80
	v_fma_f32 v199, v81, v199, v81
	v_fma_f32 v200, v82, v200, v82
	v_fma_f32 v201, v83, v201, v83
	v_mul_f32_e32 v194, 0x3f4c422a, v194
	v_mul_f32_e32 v195, 0x3f4c422a, v195
	v_mul_f32_e32 v196, 0x3f4c422a, v196
	v_mul_f32_e32 v197, 0x3f4c422a, v197
	v_mul_f32_e32 v198, 0x3f4c422a, v198
	v_mul_f32_e32 v199, 0x3f4c422a, v199
	v_mul_f32_e32 v200, 0x3f4c422a, v200
	v_mul_f32_e32 v201, 0x3f4c422a, v201
	v_add_f32_e32 v194, v194, v194
	v_add_f32_e32 v195, v195, v195
	v_add_f32_e32 v196, v196, v196
	v_add_f32_e32 v197, v197, v197
	v_add_f32_e32 v198, v198, v198
	v_add_f32_e32 v199, v199, v199
	v_add_f32_e32 v200, v200, v200
	v_add_f32_e32 v201, v201, v201
	v_mul_f32_e32 v194, 0xbfb8aa3b, v194
	v_mul_f32_e32 v195, 0xbfb8aa3b, v195
	v_mul_f32_e32 v196, 0xbfb8aa3b, v196
	v_mul_f32_e32 v197, 0xbfb8aa3b, v197
	v_mul_f32_e32 v198, 0xbfb8aa3b, v198
	v_mul_f32_e32 v199, 0xbfb8aa3b, v199
	v_mul_f32_e32 v200, 0xbfb8aa3b, v200
	v_mul_f32_e32 v201, 0xbfb8aa3b, v201
	v_exp_f32_e32 v194, v194
	v_exp_f32_e32 v195, v195
	v_exp_f32_e32 v196, v196
	v_exp_f32_e32 v197, v197
	v_exp_f32_e32 v198, v198
	v_exp_f32_e32 v199, v199
	v_exp_f32_e32 v200, v200
	v_exp_f32_e32 v201, v201
	v_add_f32_e32 v194, 1.0, v194
	v_add_f32_e32 v195, 1.0, v195
	v_add_f32_e32 v196, 1.0, v196
	v_add_f32_e32 v197, 1.0, v197
	v_add_f32_e32 v198, 1.0, v198
	v_add_f32_e32 v199, 1.0, v199
	v_add_f32_e32 v200, 1.0, v200
	v_add_f32_e32 v201, 1.0, v201
	v_rcp_f32_e32 v194, v194
	v_rcp_f32_e32 v195, v195
	v_rcp_f32_e32 v196, v196
	v_rcp_f32_e32 v197, v197
	v_rcp_f32_e32 v198, v198
	v_rcp_f32_e32 v199, v199
	v_rcp_f32_e32 v200, v200
	v_rcp_f32_e32 v201, v201
	v_mul_f32_e32 v84, v84, v194
	v_mul_f32_e32 v85, v85, v195
	v_mul_f32_e32 v86, v86, v196
	v_mul_f32_e32 v87, v87, v197
	v_mul_f32_e32 v80, v80, v198
	v_mul_f32_e32 v81, v81, v199
	v_mul_f32_e32 v82, v82, v200
	v_mul_f32_e32 v83, v83, v201
	v_cvt_pk_bf16_f32 v234, v84, v85
	v_cvt_pk_bf16_f32 v235, v86, v87
	v_cvt_pk_bf16_f32 v236, v80, v81
	v_cvt_pk_bf16_f32 v237, v82, v83
	v_add_co_u32_e32 v246, vcc, 0x10100, v244
	v_addc_co_u32_e32 v247, vcc, 0, v245, vcc
	v_permlane16_swap_b32 v234, v236
	v_permlane16_swap_b32 v235, v237
	global_store_dwordx4 v[246:247], v[234:237], off
	v_mul_f32_e32 v194, 0x3d372713, v76
	v_mul_f32_e32 v195, 0x3d372713, v77
	v_mul_f32_e32 v196, 0x3d372713, v78
	v_mul_f32_e32 v197, 0x3d372713, v79
	v_mul_f32_e32 v198, 0x3d372713, v72
	v_mul_f32_e32 v199, 0x3d372713, v73
	v_mul_f32_e32 v200, 0x3d372713, v74
	v_mul_f32_e32 v201, 0x3d372713, v75
	v_mul_f32_e32 v194, v76, v194
	v_mul_f32_e32 v195, v77, v195
	v_mul_f32_e32 v196, v78, v196
	v_mul_f32_e32 v197, v79, v197
	v_mul_f32_e32 v198, v72, v198
	v_mul_f32_e32 v199, v73, v199
	v_mul_f32_e32 v200, v74, v200
	v_mul_f32_e32 v201, v75, v201
	v_fma_f32 v194, v76, v194, v76
	v_fma_f32 v195, v77, v195, v77
	v_fma_f32 v196, v78, v196, v78
	v_fma_f32 v197, v79, v197, v79
	v_fma_f32 v198, v72, v198, v72
	v_fma_f32 v199, v73, v199, v73
	v_fma_f32 v200, v74, v200, v74
	v_fma_f32 v201, v75, v201, v75
	v_mul_f32_e32 v194, 0x3f4c422a, v194
	v_mul_f32_e32 v195, 0x3f4c422a, v195
	v_mul_f32_e32 v196, 0x3f4c422a, v196
	v_mul_f32_e32 v197, 0x3f4c422a, v197
	v_mul_f32_e32 v198, 0x3f4c422a, v198
	v_mul_f32_e32 v199, 0x3f4c422a, v199
	v_mul_f32_e32 v200, 0x3f4c422a, v200
	v_mul_f32_e32 v201, 0x3f4c422a, v201
	v_add_f32_e32 v194, v194, v194
	v_add_f32_e32 v195, v195, v195
	v_add_f32_e32 v196, v196, v196
	v_add_f32_e32 v197, v197, v197
	v_add_f32_e32 v198, v198, v198
	v_add_f32_e32 v199, v199, v199
	v_add_f32_e32 v200, v200, v200
	v_add_f32_e32 v201, v201, v201
	v_mul_f32_e32 v194, 0xbfb8aa3b, v194
	v_mul_f32_e32 v195, 0xbfb8aa3b, v195
	v_mul_f32_e32 v196, 0xbfb8aa3b, v196
	v_mul_f32_e32 v197, 0xbfb8aa3b, v197
	v_mul_f32_e32 v198, 0xbfb8aa3b, v198
	v_mul_f32_e32 v199, 0xbfb8aa3b, v199
	v_mul_f32_e32 v200, 0xbfb8aa3b, v200
	v_mul_f32_e32 v201, 0xbfb8aa3b, v201
	v_exp_f32_e32 v194, v194
	v_exp_f32_e32 v195, v195
	v_exp_f32_e32 v196, v196
	v_exp_f32_e32 v197, v197
	v_exp_f32_e32 v198, v198
	v_exp_f32_e32 v199, v199
	v_exp_f32_e32 v200, v200
	v_exp_f32_e32 v201, v201
	v_add_f32_e32 v194, 1.0, v194
	v_add_f32_e32 v195, 1.0, v195
	v_add_f32_e32 v196, 1.0, v196
	v_add_f32_e32 v197, 1.0, v197
	v_add_f32_e32 v198, 1.0, v198
	v_add_f32_e32 v199, 1.0, v199
	v_add_f32_e32 v200, 1.0, v200
	v_add_f32_e32 v201, 1.0, v201
	v_rcp_f32_e32 v194, v194
	v_rcp_f32_e32 v195, v195
	v_rcp_f32_e32 v196, v196
	v_rcp_f32_e32 v197, v197
	v_rcp_f32_e32 v198, v198
	v_rcp_f32_e32 v199, v199
	v_rcp_f32_e32 v200, v200
	v_rcp_f32_e32 v201, v201
	v_mul_f32_e32 v76, v76, v194
	v_mul_f32_e32 v77, v77, v195
	v_mul_f32_e32 v78, v78, v196
	v_mul_f32_e32 v79, v79, v197
	v_mul_f32_e32 v72, v72, v198
	v_mul_f32_e32 v73, v73, v199
	v_mul_f32_e32 v74, v74, v200
	v_mul_f32_e32 v75, v75, v201
	v_cvt_pk_bf16_f32 v230, v76, v77
	v_cvt_pk_bf16_f32 v231, v78, v79
	v_cvt_pk_bf16_f32 v232, v72, v73
	v_cvt_pk_bf16_f32 v233, v74, v75
	v_add_co_u32_e32 v246, vcc, 0x18000, v244
	v_addc_co_u32_e32 v247, vcc, 0, v245, vcc
	v_permlane16_swap_b32 v230, v232
	v_permlane16_swap_b32 v231, v233
	global_store_dwordx4 v[246:247], v[230:233], off
	v_mul_f32_e32 v194, 0x3d372713, v68
	v_mul_f32_e32 v195, 0x3d372713, v69
	v_mul_f32_e32 v196, 0x3d372713, v70
	v_mul_f32_e32 v197, 0x3d372713, v71
	v_mul_f32_e32 v198, 0x3d372713, v64
	v_mul_f32_e32 v199, 0x3d372713, v65
	v_mul_f32_e32 v200, 0x3d372713, v66
	v_mul_f32_e32 v201, 0x3d372713, v67
	v_mul_f32_e32 v194, v68, v194
	v_mul_f32_e32 v195, v69, v195
	v_mul_f32_e32 v196, v70, v196
	v_mul_f32_e32 v197, v71, v197
	v_mul_f32_e32 v198, v64, v198
	v_mul_f32_e32 v199, v65, v199
	v_mul_f32_e32 v200, v66, v200
	v_mul_f32_e32 v201, v67, v201
	v_fma_f32 v194, v68, v194, v68
	v_fma_f32 v195, v69, v195, v69
	v_fma_f32 v196, v70, v196, v70
	v_fma_f32 v197, v71, v197, v71
	v_fma_f32 v198, v64, v198, v64
	v_fma_f32 v199, v65, v199, v65
	v_fma_f32 v200, v66, v200, v66
	v_fma_f32 v201, v67, v201, v67
	v_mul_f32_e32 v194, 0x3f4c422a, v194
	v_mul_f32_e32 v195, 0x3f4c422a, v195
	v_mul_f32_e32 v196, 0x3f4c422a, v196
	v_mul_f32_e32 v197, 0x3f4c422a, v197
	v_mul_f32_e32 v198, 0x3f4c422a, v198
	v_mul_f32_e32 v199, 0x3f4c422a, v199
	v_mul_f32_e32 v200, 0x3f4c422a, v200
	v_mul_f32_e32 v201, 0x3f4c422a, v201
	v_add_f32_e32 v194, v194, v194
	v_add_f32_e32 v195, v195, v195
	v_add_f32_e32 v196, v196, v196
	v_add_f32_e32 v197, v197, v197
	v_add_f32_e32 v198, v198, v198
	v_add_f32_e32 v199, v199, v199
	v_add_f32_e32 v200, v200, v200
	v_add_f32_e32 v201, v201, v201
	v_mul_f32_e32 v194, 0xbfb8aa3b, v194
	v_mul_f32_e32 v195, 0xbfb8aa3b, v195
	v_mul_f32_e32 v196, 0xbfb8aa3b, v196
	v_mul_f32_e32 v197, 0xbfb8aa3b, v197
	v_mul_f32_e32 v198, 0xbfb8aa3b, v198
	v_mul_f32_e32 v199, 0xbfb8aa3b, v199
	v_mul_f32_e32 v200, 0xbfb8aa3b, v200
	v_mul_f32_e32 v201, 0xbfb8aa3b, v201
	v_exp_f32_e32 v194, v194
	v_exp_f32_e32 v195, v195
	v_exp_f32_e32 v196, v196
	v_exp_f32_e32 v197, v197
	v_exp_f32_e32 v198, v198
	v_exp_f32_e32 v199, v199
	v_exp_f32_e32 v200, v200
	v_exp_f32_e32 v201, v201
	v_add_f32_e32 v194, 1.0, v194
	v_add_f32_e32 v195, 1.0, v195
	v_add_f32_e32 v196, 1.0, v196
	v_add_f32_e32 v197, 1.0, v197
	v_add_f32_e32 v198, 1.0, v198
	v_add_f32_e32 v199, 1.0, v199
	v_add_f32_e32 v200, 1.0, v200
	v_add_f32_e32 v201, 1.0, v201
	v_rcp_f32_e32 v194, v194
	v_rcp_f32_e32 v195, v195
	v_rcp_f32_e32 v196, v196
	v_rcp_f32_e32 v197, v197
	v_rcp_f32_e32 v198, v198
	v_rcp_f32_e32 v199, v199
	v_rcp_f32_e32 v200, v200
	v_rcp_f32_e32 v201, v201
	v_mul_f32_e32 v68, v68, v194
	v_mul_f32_e32 v69, v69, v195
	v_mul_f32_e32 v70, v70, v196
	v_mul_f32_e32 v71, v71, v197
	v_mul_f32_e32 v64, v64, v198
	v_mul_f32_e32 v65, v65, v199
	v_mul_f32_e32 v66, v66, v200
	v_mul_f32_e32 v67, v67, v201
	v_cvt_pk_bf16_f32 v234, v68, v69
	v_cvt_pk_bf16_f32 v235, v70, v71
	v_cvt_pk_bf16_f32 v236, v64, v65
	v_cvt_pk_bf16_f32 v237, v66, v67
	v_add_co_u32_e32 v246, vcc, 0x18100, v244
	v_addc_co_u32_e32 v247, vcc, 0, v245, vcc
	v_permlane16_swap_b32 v234, v236
	v_permlane16_swap_b32 v235, v237
	global_store_dwordx4 v[246:247], v[234:237], off
	v_mul_f32_e32 v194, 0x3d372713, v60
	v_mul_f32_e32 v195, 0x3d372713, v61
	v_mul_f32_e32 v196, 0x3d372713, v62
	v_mul_f32_e32 v197, 0x3d372713, v63
	v_mul_f32_e32 v198, 0x3d372713, v56
	v_mul_f32_e32 v199, 0x3d372713, v57
	v_mul_f32_e32 v200, 0x3d372713, v58
	v_mul_f32_e32 v201, 0x3d372713, v59
	v_mul_f32_e32 v194, v60, v194
	v_mul_f32_e32 v195, v61, v195
	v_mul_f32_e32 v196, v62, v196
	v_mul_f32_e32 v197, v63, v197
	v_mul_f32_e32 v198, v56, v198
	v_mul_f32_e32 v199, v57, v199
	v_mul_f32_e32 v200, v58, v200
	v_mul_f32_e32 v201, v59, v201
	v_fma_f32 v194, v60, v194, v60
	v_fma_f32 v195, v61, v195, v61
	v_fma_f32 v196, v62, v196, v62
	v_fma_f32 v197, v63, v197, v63
	v_fma_f32 v198, v56, v198, v56
	v_fma_f32 v199, v57, v199, v57
	v_fma_f32 v200, v58, v200, v58
	v_fma_f32 v201, v59, v201, v59
	v_mul_f32_e32 v194, 0x3f4c422a, v194
	v_mul_f32_e32 v195, 0x3f4c422a, v195
	v_mul_f32_e32 v196, 0x3f4c422a, v196
	v_mul_f32_e32 v197, 0x3f4c422a, v197
	v_mul_f32_e32 v198, 0x3f4c422a, v198
	v_mul_f32_e32 v199, 0x3f4c422a, v199
	v_mul_f32_e32 v200, 0x3f4c422a, v200
	v_mul_f32_e32 v201, 0x3f4c422a, v201
	v_add_f32_e32 v194, v194, v194
	v_add_f32_e32 v195, v195, v195
	v_add_f32_e32 v196, v196, v196
	v_add_f32_e32 v197, v197, v197
	v_add_f32_e32 v198, v198, v198
	v_add_f32_e32 v199, v199, v199
	v_add_f32_e32 v200, v200, v200
	v_add_f32_e32 v201, v201, v201
	v_mul_f32_e32 v194, 0xbfb8aa3b, v194
	v_mul_f32_e32 v195, 0xbfb8aa3b, v195
	v_mul_f32_e32 v196, 0xbfb8aa3b, v196
	v_mul_f32_e32 v197, 0xbfb8aa3b, v197
	v_mul_f32_e32 v198, 0xbfb8aa3b, v198
	v_mul_f32_e32 v199, 0xbfb8aa3b, v199
	v_mul_f32_e32 v200, 0xbfb8aa3b, v200
	v_mul_f32_e32 v201, 0xbfb8aa3b, v201
	v_exp_f32_e32 v194, v194
	v_exp_f32_e32 v195, v195
	v_exp_f32_e32 v196, v196
	v_exp_f32_e32 v197, v197
	v_exp_f32_e32 v198, v198
	v_exp_f32_e32 v199, v199
	v_exp_f32_e32 v200, v200
	v_exp_f32_e32 v201, v201
	v_add_f32_e32 v194, 1.0, v194
	v_add_f32_e32 v195, 1.0, v195
	v_add_f32_e32 v196, 1.0, v196
	v_add_f32_e32 v197, 1.0, v197
	v_add_f32_e32 v198, 1.0, v198
	v_add_f32_e32 v199, 1.0, v199
	v_add_f32_e32 v200, 1.0, v200
	v_add_f32_e32 v201, 1.0, v201
	v_rcp_f32_e32 v194, v194
	v_rcp_f32_e32 v195, v195
	v_rcp_f32_e32 v196, v196
	v_rcp_f32_e32 v197, v197
	v_rcp_f32_e32 v198, v198
	v_rcp_f32_e32 v199, v199
	v_rcp_f32_e32 v200, v200
	v_rcp_f32_e32 v201, v201
	v_mul_f32_e32 v60, v60, v194
	v_mul_f32_e32 v61, v61, v195
	v_mul_f32_e32 v62, v62, v196
	v_mul_f32_e32 v63, v63, v197
	v_mul_f32_e32 v56, v56, v198
	v_mul_f32_e32 v57, v57, v199
	v_mul_f32_e32 v58, v58, v200
	v_mul_f32_e32 v59, v59, v201
	v_cvt_pk_bf16_f32 v230, v60, v61
	v_cvt_pk_bf16_f32 v231, v62, v63
	v_cvt_pk_bf16_f32 v232, v56, v57
	v_cvt_pk_bf16_f32 v233, v58, v59
	v_add_co_u32_e32 v246, vcc, 0x40000, v244
	v_addc_co_u32_e32 v247, vcc, 0, v245, vcc
	v_permlane16_swap_b32 v230, v232
	v_permlane16_swap_b32 v231, v233
	global_store_dwordx4 v[246:247], v[230:233], off
	v_mul_f32_e32 v194, 0x3d372713, v52
	v_mul_f32_e32 v195, 0x3d372713, v53
	v_mul_f32_e32 v196, 0x3d372713, v54
	v_mul_f32_e32 v197, 0x3d372713, v55
	v_mul_f32_e32 v198, 0x3d372713, v48
	v_mul_f32_e32 v199, 0x3d372713, v49
	v_mul_f32_e32 v200, 0x3d372713, v50
	v_mul_f32_e32 v201, 0x3d372713, v51
	v_mul_f32_e32 v194, v52, v194
	v_mul_f32_e32 v195, v53, v195
	v_mul_f32_e32 v196, v54, v196
	v_mul_f32_e32 v197, v55, v197
	v_mul_f32_e32 v198, v48, v198
	v_mul_f32_e32 v199, v49, v199
	v_mul_f32_e32 v200, v50, v200
	v_mul_f32_e32 v201, v51, v201
	v_fma_f32 v194, v52, v194, v52
	v_fma_f32 v195, v53, v195, v53
	v_fma_f32 v196, v54, v196, v54
	v_fma_f32 v197, v55, v197, v55
	v_fma_f32 v198, v48, v198, v48
	v_fma_f32 v199, v49, v199, v49
	v_fma_f32 v200, v50, v200, v50
	v_fma_f32 v201, v51, v201, v51
	v_mul_f32_e32 v194, 0x3f4c422a, v194
	v_mul_f32_e32 v195, 0x3f4c422a, v195
	v_mul_f32_e32 v196, 0x3f4c422a, v196
	v_mul_f32_e32 v197, 0x3f4c422a, v197
	v_mul_f32_e32 v198, 0x3f4c422a, v198
	v_mul_f32_e32 v199, 0x3f4c422a, v199
	v_mul_f32_e32 v200, 0x3f4c422a, v200
	v_mul_f32_e32 v201, 0x3f4c422a, v201
	v_add_f32_e32 v194, v194, v194
	v_add_f32_e32 v195, v195, v195
	v_add_f32_e32 v196, v196, v196
	v_add_f32_e32 v197, v197, v197
	v_add_f32_e32 v198, v198, v198
	v_add_f32_e32 v199, v199, v199
	v_add_f32_e32 v200, v200, v200
	v_add_f32_e32 v201, v201, v201
	v_mul_f32_e32 v194, 0xbfb8aa3b, v194
	v_mul_f32_e32 v195, 0xbfb8aa3b, v195
	v_mul_f32_e32 v196, 0xbfb8aa3b, v196
	v_mul_f32_e32 v197, 0xbfb8aa3b, v197
	v_mul_f32_e32 v198, 0xbfb8aa3b, v198
	v_mul_f32_e32 v199, 0xbfb8aa3b, v199
	v_mul_f32_e32 v200, 0xbfb8aa3b, v200
	v_mul_f32_e32 v201, 0xbfb8aa3b, v201
	v_exp_f32_e32 v194, v194
	v_exp_f32_e32 v195, v195
	v_exp_f32_e32 v196, v196
	v_exp_f32_e32 v197, v197
	v_exp_f32_e32 v198, v198
	v_exp_f32_e32 v199, v199
	v_exp_f32_e32 v200, v200
	v_exp_f32_e32 v201, v201
	v_add_f32_e32 v194, 1.0, v194
	v_add_f32_e32 v195, 1.0, v195
	v_add_f32_e32 v196, 1.0, v196
	v_add_f32_e32 v197, 1.0, v197
	v_add_f32_e32 v198, 1.0, v198
	v_add_f32_e32 v199, 1.0, v199
	v_add_f32_e32 v200, 1.0, v200
	v_add_f32_e32 v201, 1.0, v201
	v_rcp_f32_e32 v194, v194
	v_rcp_f32_e32 v195, v195
	v_rcp_f32_e32 v196, v196
	v_rcp_f32_e32 v197, v197
	v_rcp_f32_e32 v198, v198
	v_rcp_f32_e32 v199, v199
	v_rcp_f32_e32 v200, v200
	v_rcp_f32_e32 v201, v201
	v_mul_f32_e32 v52, v52, v194
	v_mul_f32_e32 v53, v53, v195
	v_mul_f32_e32 v54, v54, v196
	v_mul_f32_e32 v55, v55, v197
	v_mul_f32_e32 v48, v48, v198
	v_mul_f32_e32 v49, v49, v199
	v_mul_f32_e32 v50, v50, v200
	v_mul_f32_e32 v51, v51, v201
	v_cvt_pk_bf16_f32 v234, v52, v53
	v_cvt_pk_bf16_f32 v235, v54, v55
	v_cvt_pk_bf16_f32 v236, v48, v49
	v_cvt_pk_bf16_f32 v237, v50, v51
	v_add_co_u32_e32 v246, vcc, 0x40100, v244
	v_addc_co_u32_e32 v247, vcc, 0, v245, vcc
	v_permlane16_swap_b32 v234, v236
	v_permlane16_swap_b32 v235, v237
	global_store_dwordx4 v[246:247], v[234:237], off
	v_mul_f32_e32 v194, 0x3d372713, v44
	v_mul_f32_e32 v195, 0x3d372713, v45
	v_mul_f32_e32 v196, 0x3d372713, v46
	v_mul_f32_e32 v197, 0x3d372713, v47
	v_mul_f32_e32 v198, 0x3d372713, v40
	v_mul_f32_e32 v199, 0x3d372713, v41
	v_mul_f32_e32 v200, 0x3d372713, v42
	v_mul_f32_e32 v201, 0x3d372713, v43
	v_mul_f32_e32 v194, v44, v194
	v_mul_f32_e32 v195, v45, v195
	v_mul_f32_e32 v196, v46, v196
	v_mul_f32_e32 v197, v47, v197
	v_mul_f32_e32 v198, v40, v198
	v_mul_f32_e32 v199, v41, v199
	v_mul_f32_e32 v200, v42, v200
	v_mul_f32_e32 v201, v43, v201
	v_fma_f32 v194, v44, v194, v44
	v_fma_f32 v195, v45, v195, v45
	v_fma_f32 v196, v46, v196, v46
	v_fma_f32 v197, v47, v197, v47
	v_fma_f32 v198, v40, v198, v40
	v_fma_f32 v199, v41, v199, v41
	v_fma_f32 v200, v42, v200, v42
	v_fma_f32 v201, v43, v201, v43
	v_mul_f32_e32 v194, 0x3f4c422a, v194
	v_mul_f32_e32 v195, 0x3f4c422a, v195
	v_mul_f32_e32 v196, 0x3f4c422a, v196
	v_mul_f32_e32 v197, 0x3f4c422a, v197
	v_mul_f32_e32 v198, 0x3f4c422a, v198
	v_mul_f32_e32 v199, 0x3f4c422a, v199
	v_mul_f32_e32 v200, 0x3f4c422a, v200
	v_mul_f32_e32 v201, 0x3f4c422a, v201
	v_add_f32_e32 v194, v194, v194
	v_add_f32_e32 v195, v195, v195
	v_add_f32_e32 v196, v196, v196
	v_add_f32_e32 v197, v197, v197
	v_add_f32_e32 v198, v198, v198
	v_add_f32_e32 v199, v199, v199
	v_add_f32_e32 v200, v200, v200
	v_add_f32_e32 v201, v201, v201
	v_mul_f32_e32 v194, 0xbfb8aa3b, v194
	v_mul_f32_e32 v195, 0xbfb8aa3b, v195
	v_mul_f32_e32 v196, 0xbfb8aa3b, v196
	v_mul_f32_e32 v197, 0xbfb8aa3b, v197
	v_mul_f32_e32 v198, 0xbfb8aa3b, v198
	v_mul_f32_e32 v199, 0xbfb8aa3b, v199
	v_mul_f32_e32 v200, 0xbfb8aa3b, v200
	v_mul_f32_e32 v201, 0xbfb8aa3b, v201
	v_exp_f32_e32 v194, v194
	v_exp_f32_e32 v195, v195
	v_exp_f32_e32 v196, v196
	v_exp_f32_e32 v197, v197
	v_exp_f32_e32 v198, v198
	v_exp_f32_e32 v199, v199
	v_exp_f32_e32 v200, v200
	v_exp_f32_e32 v201, v201
	v_add_f32_e32 v194, 1.0, v194
	v_add_f32_e32 v195, 1.0, v195
	v_add_f32_e32 v196, 1.0, v196
	v_add_f32_e32 v197, 1.0, v197
	v_add_f32_e32 v198, 1.0, v198
	v_add_f32_e32 v199, 1.0, v199
	v_add_f32_e32 v200, 1.0, v200
	v_add_f32_e32 v201, 1.0, v201
	v_rcp_f32_e32 v194, v194
	v_rcp_f32_e32 v195, v195
	v_rcp_f32_e32 v196, v196
	v_rcp_f32_e32 v197, v197
	v_rcp_f32_e32 v198, v198
	v_rcp_f32_e32 v199, v199
	v_rcp_f32_e32 v200, v200
	v_rcp_f32_e32 v201, v201
	v_mul_f32_e32 v44, v44, v194
	v_mul_f32_e32 v45, v45, v195
	v_mul_f32_e32 v46, v46, v196
	v_mul_f32_e32 v47, v47, v197
	v_mul_f32_e32 v40, v40, v198
	v_mul_f32_e32 v41, v41, v199
	v_mul_f32_e32 v42, v42, v200
	v_mul_f32_e32 v43, v43, v201
	v_cvt_pk_bf16_f32 v230, v44, v45
	v_cvt_pk_bf16_f32 v231, v46, v47
	v_cvt_pk_bf16_f32 v232, v40, v41
	v_cvt_pk_bf16_f32 v233, v42, v43
	v_add_co_u32_e32 v246, vcc, 0x48000, v244
	v_addc_co_u32_e32 v247, vcc, 0, v245, vcc
	v_permlane16_swap_b32 v230, v232
	v_permlane16_swap_b32 v231, v233
	global_store_dwordx4 v[246:247], v[230:233], off
	v_mul_f32_e32 v194, 0x3d372713, v36
	v_mul_f32_e32 v195, 0x3d372713, v37
	v_mul_f32_e32 v196, 0x3d372713, v38
	v_mul_f32_e32 v197, 0x3d372713, v39
	v_mul_f32_e32 v198, 0x3d372713, v32
	v_mul_f32_e32 v199, 0x3d372713, v33
	v_mul_f32_e32 v200, 0x3d372713, v34
	v_mul_f32_e32 v201, 0x3d372713, v35
	v_mul_f32_e32 v194, v36, v194
	v_mul_f32_e32 v195, v37, v195
	v_mul_f32_e32 v196, v38, v196
	v_mul_f32_e32 v197, v39, v197
	v_mul_f32_e32 v198, v32, v198
	v_mul_f32_e32 v199, v33, v199
	v_mul_f32_e32 v200, v34, v200
	v_mul_f32_e32 v201, v35, v201
	v_fma_f32 v194, v36, v194, v36
	v_fma_f32 v195, v37, v195, v37
	v_fma_f32 v196, v38, v196, v38
	v_fma_f32 v197, v39, v197, v39
	v_fma_f32 v198, v32, v198, v32
	v_fma_f32 v199, v33, v199, v33
	v_fma_f32 v200, v34, v200, v34
	v_fma_f32 v201, v35, v201, v35
	v_mul_f32_e32 v194, 0x3f4c422a, v194
	v_mul_f32_e32 v195, 0x3f4c422a, v195
	v_mul_f32_e32 v196, 0x3f4c422a, v196
	v_mul_f32_e32 v197, 0x3f4c422a, v197
	v_mul_f32_e32 v198, 0x3f4c422a, v198
	v_mul_f32_e32 v199, 0x3f4c422a, v199
	v_mul_f32_e32 v200, 0x3f4c422a, v200
	v_mul_f32_e32 v201, 0x3f4c422a, v201
	v_add_f32_e32 v194, v194, v194
	v_add_f32_e32 v195, v195, v195
	v_add_f32_e32 v196, v196, v196
	v_add_f32_e32 v197, v197, v197
	v_add_f32_e32 v198, v198, v198
	v_add_f32_e32 v199, v199, v199
	v_add_f32_e32 v200, v200, v200
	v_add_f32_e32 v201, v201, v201
	v_mul_f32_e32 v194, 0xbfb8aa3b, v194
	v_mul_f32_e32 v195, 0xbfb8aa3b, v195
	v_mul_f32_e32 v196, 0xbfb8aa3b, v196
	v_mul_f32_e32 v197, 0xbfb8aa3b, v197
	v_mul_f32_e32 v198, 0xbfb8aa3b, v198
	v_mul_f32_e32 v199, 0xbfb8aa3b, v199
	v_mul_f32_e32 v200, 0xbfb8aa3b, v200
	v_mul_f32_e32 v201, 0xbfb8aa3b, v201
	v_exp_f32_e32 v194, v194
	v_exp_f32_e32 v195, v195
	v_exp_f32_e32 v196, v196
	v_exp_f32_e32 v197, v197
	v_exp_f32_e32 v198, v198
	v_exp_f32_e32 v199, v199
	v_exp_f32_e32 v200, v200
	v_exp_f32_e32 v201, v201
	v_add_f32_e32 v194, 1.0, v194
	v_add_f32_e32 v195, 1.0, v195
	v_add_f32_e32 v196, 1.0, v196
	v_add_f32_e32 v197, 1.0, v197
	v_add_f32_e32 v198, 1.0, v198
	v_add_f32_e32 v199, 1.0, v199
	v_add_f32_e32 v200, 1.0, v200
	v_add_f32_e32 v201, 1.0, v201
	v_rcp_f32_e32 v194, v194
	v_rcp_f32_e32 v195, v195
	v_rcp_f32_e32 v196, v196
	v_rcp_f32_e32 v197, v197
	v_rcp_f32_e32 v198, v198
	v_rcp_f32_e32 v199, v199
	v_rcp_f32_e32 v200, v200
	v_rcp_f32_e32 v201, v201
	v_mul_f32_e32 v36, v36, v194
	v_mul_f32_e32 v37, v37, v195
	v_mul_f32_e32 v38, v38, v196
	v_mul_f32_e32 v39, v39, v197
	v_mul_f32_e32 v32, v32, v198
	v_mul_f32_e32 v33, v33, v199
	v_mul_f32_e32 v34, v34, v200
	v_mul_f32_e32 v35, v35, v201
	v_cvt_pk_bf16_f32 v234, v36, v37
	v_cvt_pk_bf16_f32 v235, v38, v39
	v_cvt_pk_bf16_f32 v236, v32, v33
	v_cvt_pk_bf16_f32 v237, v34, v35
	v_add_co_u32_e32 v246, vcc, 0x48100, v244
	v_addc_co_u32_e32 v247, vcc, 0, v245, vcc
	v_permlane16_swap_b32 v234, v236
	v_permlane16_swap_b32 v235, v237
	global_store_dwordx4 v[246:247], v[234:237], off
	v_mul_f32_e32 v194, 0x3d372713, v28
	v_mul_f32_e32 v195, 0x3d372713, v29
	v_mul_f32_e32 v196, 0x3d372713, v30
	v_mul_f32_e32 v197, 0x3d372713, v31
	v_mul_f32_e32 v198, 0x3d372713, v24
	v_mul_f32_e32 v199, 0x3d372713, v25
	v_mul_f32_e32 v200, 0x3d372713, v26
	v_mul_f32_e32 v201, 0x3d372713, v27
	v_mul_f32_e32 v194, v28, v194
	v_mul_f32_e32 v195, v29, v195
	v_mul_f32_e32 v196, v30, v196
	v_mul_f32_e32 v197, v31, v197
	v_mul_f32_e32 v198, v24, v198
	v_mul_f32_e32 v199, v25, v199
	v_mul_f32_e32 v200, v26, v200
	v_mul_f32_e32 v201, v27, v201
	v_fma_f32 v194, v28, v194, v28
	v_fma_f32 v195, v29, v195, v29
	v_fma_f32 v196, v30, v196, v30
	v_fma_f32 v197, v31, v197, v31
	v_fma_f32 v198, v24, v198, v24
	v_fma_f32 v199, v25, v199, v25
	v_fma_f32 v200, v26, v200, v26
	v_fma_f32 v201, v27, v201, v27
	v_mul_f32_e32 v194, 0x3f4c422a, v194
	v_mul_f32_e32 v195, 0x3f4c422a, v195
	v_mul_f32_e32 v196, 0x3f4c422a, v196
	v_mul_f32_e32 v197, 0x3f4c422a, v197
	v_mul_f32_e32 v198, 0x3f4c422a, v198
	v_mul_f32_e32 v199, 0x3f4c422a, v199
	v_mul_f32_e32 v200, 0x3f4c422a, v200
	v_mul_f32_e32 v201, 0x3f4c422a, v201
	v_add_f32_e32 v194, v194, v194
	v_add_f32_e32 v195, v195, v195
	v_add_f32_e32 v196, v196, v196
	v_add_f32_e32 v197, v197, v197
	v_add_f32_e32 v198, v198, v198
	v_add_f32_e32 v199, v199, v199
	v_add_f32_e32 v200, v200, v200
	v_add_f32_e32 v201, v201, v201
	v_mul_f32_e32 v194, 0xbfb8aa3b, v194
	v_mul_f32_e32 v195, 0xbfb8aa3b, v195
	v_mul_f32_e32 v196, 0xbfb8aa3b, v196
	v_mul_f32_e32 v197, 0xbfb8aa3b, v197
	v_mul_f32_e32 v198, 0xbfb8aa3b, v198
	v_mul_f32_e32 v199, 0xbfb8aa3b, v199
	v_mul_f32_e32 v200, 0xbfb8aa3b, v200
	v_mul_f32_e32 v201, 0xbfb8aa3b, v201
	v_exp_f32_e32 v194, v194
	v_exp_f32_e32 v195, v195
	v_exp_f32_e32 v196, v196
	v_exp_f32_e32 v197, v197
	v_exp_f32_e32 v198, v198
	v_exp_f32_e32 v199, v199
	v_exp_f32_e32 v200, v200
	v_exp_f32_e32 v201, v201
	v_add_f32_e32 v194, 1.0, v194
	v_add_f32_e32 v195, 1.0, v195
	v_add_f32_e32 v196, 1.0, v196
	v_add_f32_e32 v197, 1.0, v197
	v_add_f32_e32 v198, 1.0, v198
	v_add_f32_e32 v199, 1.0, v199
	v_add_f32_e32 v200, 1.0, v200
	v_add_f32_e32 v201, 1.0, v201
	v_rcp_f32_e32 v194, v194
	v_rcp_f32_e32 v195, v195
	v_rcp_f32_e32 v196, v196
	v_rcp_f32_e32 v197, v197
	v_rcp_f32_e32 v198, v198
	v_rcp_f32_e32 v199, v199
	v_rcp_f32_e32 v200, v200
	v_rcp_f32_e32 v201, v201
	v_mul_f32_e32 v28, v28, v194
	v_mul_f32_e32 v29, v29, v195
	v_mul_f32_e32 v30, v30, v196
	v_mul_f32_e32 v31, v31, v197
	v_mul_f32_e32 v24, v24, v198
	v_mul_f32_e32 v25, v25, v199
	v_mul_f32_e32 v26, v26, v200
	v_mul_f32_e32 v27, v27, v201
	v_cvt_pk_bf16_f32 v230, v28, v29
	v_cvt_pk_bf16_f32 v231, v30, v31
	v_cvt_pk_bf16_f32 v232, v24, v25
	v_cvt_pk_bf16_f32 v233, v26, v27
	v_add_co_u32_e32 v246, vcc, 0x50000, v244
	v_addc_co_u32_e32 v247, vcc, 0, v245, vcc
	v_permlane16_swap_b32 v230, v232
	v_permlane16_swap_b32 v231, v233
	global_store_dwordx4 v[246:247], v[230:233], off
	v_mul_f32_e32 v194, 0x3d372713, v20
	v_mul_f32_e32 v195, 0x3d372713, v21
	v_mul_f32_e32 v196, 0x3d372713, v22
	v_mul_f32_e32 v197, 0x3d372713, v23
	v_mul_f32_e32 v198, 0x3d372713, v16
	v_mul_f32_e32 v199, 0x3d372713, v17
	v_mul_f32_e32 v200, 0x3d372713, v18
	v_mul_f32_e32 v201, 0x3d372713, v19
	v_mul_f32_e32 v194, v20, v194
	v_mul_f32_e32 v195, v21, v195
	v_mul_f32_e32 v196, v22, v196
	v_mul_f32_e32 v197, v23, v197
	v_mul_f32_e32 v198, v16, v198
	v_mul_f32_e32 v199, v17, v199
	v_mul_f32_e32 v200, v18, v200
	v_mul_f32_e32 v201, v19, v201
	v_fma_f32 v194, v20, v194, v20
	v_fma_f32 v195, v21, v195, v21
	v_fma_f32 v196, v22, v196, v22
	v_fma_f32 v197, v23, v197, v23
	v_fma_f32 v198, v16, v198, v16
	v_fma_f32 v199, v17, v199, v17
	v_fma_f32 v200, v18, v200, v18
	v_fma_f32 v201, v19, v201, v19
	v_mul_f32_e32 v194, 0x3f4c422a, v194
	v_mul_f32_e32 v195, 0x3f4c422a, v195
	v_mul_f32_e32 v196, 0x3f4c422a, v196
	v_mul_f32_e32 v197, 0x3f4c422a, v197
	v_mul_f32_e32 v198, 0x3f4c422a, v198
	v_mul_f32_e32 v199, 0x3f4c422a, v199
	v_mul_f32_e32 v200, 0x3f4c422a, v200
	v_mul_f32_e32 v201, 0x3f4c422a, v201
	v_add_f32_e32 v194, v194, v194
	v_add_f32_e32 v195, v195, v195
	v_add_f32_e32 v196, v196, v196
	v_add_f32_e32 v197, v197, v197
	v_add_f32_e32 v198, v198, v198
	v_add_f32_e32 v199, v199, v199
	v_add_f32_e32 v200, v200, v200
	v_add_f32_e32 v201, v201, v201
	v_mul_f32_e32 v194, 0xbfb8aa3b, v194
	v_mul_f32_e32 v195, 0xbfb8aa3b, v195
	v_mul_f32_e32 v196, 0xbfb8aa3b, v196
	v_mul_f32_e32 v197, 0xbfb8aa3b, v197
	v_mul_f32_e32 v198, 0xbfb8aa3b, v198
	v_mul_f32_e32 v199, 0xbfb8aa3b, v199
	v_mul_f32_e32 v200, 0xbfb8aa3b, v200
	v_mul_f32_e32 v201, 0xbfb8aa3b, v201
	v_exp_f32_e32 v194, v194
	v_exp_f32_e32 v195, v195
	v_exp_f32_e32 v196, v196
	v_exp_f32_e32 v197, v197
	v_exp_f32_e32 v198, v198
	v_exp_f32_e32 v199, v199
	v_exp_f32_e32 v200, v200
	v_exp_f32_e32 v201, v201
	v_add_f32_e32 v194, 1.0, v194
	v_add_f32_e32 v195, 1.0, v195
	v_add_f32_e32 v196, 1.0, v196
	v_add_f32_e32 v197, 1.0, v197
	v_add_f32_e32 v198, 1.0, v198
	v_add_f32_e32 v199, 1.0, v199
	v_add_f32_e32 v200, 1.0, v200
	v_add_f32_e32 v201, 1.0, v201
	v_rcp_f32_e32 v194, v194
	v_rcp_f32_e32 v195, v195
	v_rcp_f32_e32 v196, v196
	v_rcp_f32_e32 v197, v197
	v_rcp_f32_e32 v198, v198
	v_rcp_f32_e32 v199, v199
	v_rcp_f32_e32 v200, v200
	v_rcp_f32_e32 v201, v201
	v_mul_f32_e32 v20, v20, v194
	v_mul_f32_e32 v21, v21, v195
	v_mul_f32_e32 v22, v22, v196
	v_mul_f32_e32 v23, v23, v197
	v_mul_f32_e32 v16, v16, v198
	v_mul_f32_e32 v17, v17, v199
	v_mul_f32_e32 v18, v18, v200
	v_mul_f32_e32 v19, v19, v201
	v_cvt_pk_bf16_f32 v234, v20, v21
	v_cvt_pk_bf16_f32 v235, v22, v23
	v_cvt_pk_bf16_f32 v236, v16, v17
	v_cvt_pk_bf16_f32 v237, v18, v19
	v_add_co_u32_e32 v246, vcc, 0x50100, v244
	v_addc_co_u32_e32 v247, vcc, 0, v245, vcc
	v_permlane16_swap_b32 v234, v236
	v_permlane16_swap_b32 v235, v237
	global_store_dwordx4 v[246:247], v[234:237], off
	v_mul_f32_e32 v194, 0x3d372713, v12
	v_mul_f32_e32 v195, 0x3d372713, v13
	v_mul_f32_e32 v196, 0x3d372713, v14
	v_mul_f32_e32 v197, 0x3d372713, v15
	v_mul_f32_e32 v198, 0x3d372713, v8
	v_mul_f32_e32 v199, 0x3d372713, v9
	v_mul_f32_e32 v200, 0x3d372713, v10
	v_mul_f32_e32 v201, 0x3d372713, v11
	v_mul_f32_e32 v194, v12, v194
	v_mul_f32_e32 v195, v13, v195
	v_mul_f32_e32 v196, v14, v196
	v_mul_f32_e32 v197, v15, v197
	v_mul_f32_e32 v198, v8, v198
	v_mul_f32_e32 v199, v9, v199
	v_mul_f32_e32 v200, v10, v200
	v_mul_f32_e32 v201, v11, v201
	v_fma_f32 v194, v12, v194, v12
	v_fma_f32 v195, v13, v195, v13
	v_fma_f32 v196, v14, v196, v14
	v_fma_f32 v197, v15, v197, v15
	v_fma_f32 v198, v8, v198, v8
	v_fma_f32 v199, v9, v199, v9
	v_fma_f32 v200, v10, v200, v10
	v_fma_f32 v201, v11, v201, v11
	v_mul_f32_e32 v194, 0x3f4c422a, v194
	v_mul_f32_e32 v195, 0x3f4c422a, v195
	v_mul_f32_e32 v196, 0x3f4c422a, v196
	v_mul_f32_e32 v197, 0x3f4c422a, v197
	v_mul_f32_e32 v198, 0x3f4c422a, v198
	v_mul_f32_e32 v199, 0x3f4c422a, v199
	v_mul_f32_e32 v200, 0x3f4c422a, v200
	v_mul_f32_e32 v201, 0x3f4c422a, v201
	v_add_f32_e32 v194, v194, v194
	v_add_f32_e32 v195, v195, v195
	v_add_f32_e32 v196, v196, v196
	v_add_f32_e32 v197, v197, v197
	v_add_f32_e32 v198, v198, v198
	v_add_f32_e32 v199, v199, v199
	v_add_f32_e32 v200, v200, v200
	v_add_f32_e32 v201, v201, v201
	v_mul_f32_e32 v194, 0xbfb8aa3b, v194
	v_mul_f32_e32 v195, 0xbfb8aa3b, v195
	v_mul_f32_e32 v196, 0xbfb8aa3b, v196
	v_mul_f32_e32 v197, 0xbfb8aa3b, v197
	v_mul_f32_e32 v198, 0xbfb8aa3b, v198
	v_mul_f32_e32 v199, 0xbfb8aa3b, v199
	v_mul_f32_e32 v200, 0xbfb8aa3b, v200
	v_mul_f32_e32 v201, 0xbfb8aa3b, v201
	v_exp_f32_e32 v194, v194
	v_exp_f32_e32 v195, v195
	v_exp_f32_e32 v196, v196
	v_exp_f32_e32 v197, v197
	v_exp_f32_e32 v198, v198
	v_exp_f32_e32 v199, v199
	v_exp_f32_e32 v200, v200
	v_exp_f32_e32 v201, v201
	v_add_f32_e32 v194, 1.0, v194
	v_add_f32_e32 v195, 1.0, v195
	v_add_f32_e32 v196, 1.0, v196
	v_add_f32_e32 v197, 1.0, v197
	v_add_f32_e32 v198, 1.0, v198
	v_add_f32_e32 v199, 1.0, v199
	v_add_f32_e32 v200, 1.0, v200
	v_add_f32_e32 v201, 1.0, v201
	v_rcp_f32_e32 v194, v194
	v_rcp_f32_e32 v195, v195
	v_rcp_f32_e32 v196, v196
	v_rcp_f32_e32 v197, v197
	v_rcp_f32_e32 v198, v198
	v_rcp_f32_e32 v199, v199
	v_rcp_f32_e32 v200, v200
	v_rcp_f32_e32 v201, v201
	v_mul_f32_e32 v12, v12, v194
	v_mul_f32_e32 v13, v13, v195
	v_mul_f32_e32 v14, v14, v196
	v_mul_f32_e32 v15, v15, v197
	v_mul_f32_e32 v8, v8, v198
	v_mul_f32_e32 v9, v9, v199
	v_mul_f32_e32 v10, v10, v200
	v_mul_f32_e32 v11, v11, v201
	v_cvt_pk_bf16_f32 v230, v12, v13
	v_cvt_pk_bf16_f32 v231, v14, v15
	v_cvt_pk_bf16_f32 v232, v8, v9
	v_cvt_pk_bf16_f32 v233, v10, v11
	v_add_co_u32_e32 v246, vcc, 0x58000, v244
	v_addc_co_u32_e32 v247, vcc, 0, v245, vcc
	v_permlane16_swap_b32 v230, v232
	v_permlane16_swap_b32 v231, v233
	global_store_dwordx4 v[246:247], v[230:233], off
	v_mul_f32_e32 v194, 0x3d372713, v4
	v_mul_f32_e32 v195, 0x3d372713, v5
	v_mul_f32_e32 v196, 0x3d372713, v6
	v_mul_f32_e32 v197, 0x3d372713, v7
	v_mul_f32_e32 v198, 0x3d372713, v0
	v_mul_f32_e32 v199, 0x3d372713, v1
	v_mul_f32_e32 v200, 0x3d372713, v2
	v_mul_f32_e32 v201, 0x3d372713, v3
	v_mul_f32_e32 v194, v4, v194
	v_mul_f32_e32 v195, v5, v195
	v_mul_f32_e32 v196, v6, v196
	v_mul_f32_e32 v197, v7, v197
	v_mul_f32_e32 v198, v0, v198
	v_mul_f32_e32 v199, v1, v199
	v_mul_f32_e32 v200, v2, v200
	v_mul_f32_e32 v201, v3, v201
	v_fma_f32 v194, v4, v194, v4
	v_fma_f32 v195, v5, v195, v5
	v_fma_f32 v196, v6, v196, v6
	v_fma_f32 v197, v7, v197, v7
	v_fma_f32 v198, v0, v198, v0
	v_fma_f32 v199, v1, v199, v1
	v_fma_f32 v200, v2, v200, v2
	v_fma_f32 v201, v3, v201, v3
	v_mul_f32_e32 v194, 0x3f4c422a, v194
	v_mul_f32_e32 v195, 0x3f4c422a, v195
	v_mul_f32_e32 v196, 0x3f4c422a, v196
	v_mul_f32_e32 v197, 0x3f4c422a, v197
	v_mul_f32_e32 v198, 0x3f4c422a, v198
	v_mul_f32_e32 v199, 0x3f4c422a, v199
	v_mul_f32_e32 v200, 0x3f4c422a, v200
	v_mul_f32_e32 v201, 0x3f4c422a, v201
	v_add_f32_e32 v194, v194, v194
	v_add_f32_e32 v195, v195, v195
	v_add_f32_e32 v196, v196, v196
	v_add_f32_e32 v197, v197, v197
	v_add_f32_e32 v198, v198, v198
	v_add_f32_e32 v199, v199, v199
	v_add_f32_e32 v200, v200, v200
	v_add_f32_e32 v201, v201, v201
	v_mul_f32_e32 v194, 0xbfb8aa3b, v194
	v_mul_f32_e32 v195, 0xbfb8aa3b, v195
	v_mul_f32_e32 v196, 0xbfb8aa3b, v196
	v_mul_f32_e32 v197, 0xbfb8aa3b, v197
	v_mul_f32_e32 v198, 0xbfb8aa3b, v198
	v_mul_f32_e32 v199, 0xbfb8aa3b, v199
	v_mul_f32_e32 v200, 0xbfb8aa3b, v200
	v_mul_f32_e32 v201, 0xbfb8aa3b, v201
	v_exp_f32_e32 v194, v194
	v_exp_f32_e32 v195, v195
	v_exp_f32_e32 v196, v196
	v_exp_f32_e32 v197, v197
	v_exp_f32_e32 v198, v198
	v_exp_f32_e32 v199, v199
	v_exp_f32_e32 v200, v200
	v_exp_f32_e32 v201, v201
	v_add_f32_e32 v194, 1.0, v194
	v_add_f32_e32 v195, 1.0, v195
	v_add_f32_e32 v196, 1.0, v196
	v_add_f32_e32 v197, 1.0, v197
	v_add_f32_e32 v198, 1.0, v198
	v_add_f32_e32 v199, 1.0, v199
	v_add_f32_e32 v200, 1.0, v200
	v_add_f32_e32 v201, 1.0, v201
	v_rcp_f32_e32 v194, v194
	v_rcp_f32_e32 v195, v195
	v_rcp_f32_e32 v196, v196
	v_rcp_f32_e32 v197, v197
	v_rcp_f32_e32 v198, v198
	v_rcp_f32_e32 v199, v199
	v_rcp_f32_e32 v200, v200
	v_rcp_f32_e32 v201, v201
	v_mul_f32_e32 v4, v4, v194
	v_mul_f32_e32 v5, v5, v195
	v_mul_f32_e32 v6, v6, v196
	v_mul_f32_e32 v7, v7, v197
	v_mul_f32_e32 v0, v0, v198
	v_mul_f32_e32 v1, v1, v199
	v_mul_f32_e32 v2, v2, v200
	v_mul_f32_e32 v3, v3, v201
	v_cvt_pk_bf16_f32 v234, v4, v5
	v_cvt_pk_bf16_f32 v235, v6, v7
	v_cvt_pk_bf16_f32 v236, v0, v1
	v_cvt_pk_bf16_f32 v237, v2, v3
	v_add_co_u32_e32 v246, vcc, 0x58100, v244
	v_addc_co_u32_e32 v247, vcc, 0, v245, vcc
	v_permlane16_swap_b32 v234, v236
	v_permlane16_swap_b32 v235, v237
	global_store_dwordx4 v[246:247], v[234:237], off
	s_branch .LBB0_1065
.Llru_plain:
	v_cvt_pk_bf16_f32 v230, v124, v125
	v_cvt_pk_bf16_f32 v231, v126, v127
	v_cvt_pk_bf16_f32 v232, v120, v121
	v_cvt_pk_bf16_f32 v233, v122, v123
	s_nop 1
	v_permlane16_swap_b32 v230, v232
	v_permlane16_swap_b32 v231, v233
	global_store_dwordx4 v[244:245], v[230:233], off
	v_cvt_pk_bf16_f32 v234, v116, v117
	v_cvt_pk_bf16_f32 v235, v118, v119
	v_cvt_pk_bf16_f32 v236, v112, v113
	v_cvt_pk_bf16_f32 v237, v114, v115
	v_add_co_u32_e32 v246, vcc, 0x100, v244
	v_addc_co_u32_e32 v247, vcc, 0, v245, vcc
	v_permlane16_swap_b32 v234, v236
	v_permlane16_swap_b32 v235, v237
	global_store_dwordx4 v[246:247], v[234:237], off
	v_cvt_pk_bf16_f32 v230, v108, v109
	v_cvt_pk_bf16_f32 v231, v110, v111
	v_cvt_pk_bf16_f32 v232, v104, v105
	v_cvt_pk_bf16_f32 v233, v106, v107
	v_add_co_u32_e32 v246, vcc, 0x8000, v244
	v_addc_co_u32_e32 v247, vcc, 0, v245, vcc
	v_permlane16_swap_b32 v230, v232
	v_permlane16_swap_b32 v231, v233
	global_store_dwordx4 v[246:247], v[230:233], off
	v_cvt_pk_bf16_f32 v234, v100, v101
	v_cvt_pk_bf16_f32 v235, v102, v103
	v_cvt_pk_bf16_f32 v236, v96, v97
	v_cvt_pk_bf16_f32 v237, v98, v99
	v_add_co_u32_e32 v246, vcc, 0x8100, v244
	v_addc_co_u32_e32 v247, vcc, 0, v245, vcc
	v_permlane16_swap_b32 v234, v236
	v_permlane16_swap_b32 v235, v237
	global_store_dwordx4 v[246:247], v[234:237], off
	v_cvt_pk_bf16_f32 v230, v92, v93
	v_cvt_pk_bf16_f32 v231, v94, v95
	v_cvt_pk_bf16_f32 v232, v88, v89
	v_cvt_pk_bf16_f32 v233, v90, v91
	v_add_co_u32_e32 v246, vcc, 0x10000, v244
	v_addc_co_u32_e32 v247, vcc, 0, v245, vcc
	v_permlane16_swap_b32 v230, v232
	v_permlane16_swap_b32 v231, v233
	global_store_dwordx4 v[246:247], v[230:233], off
	v_cvt_pk_bf16_f32 v234, v84, v85
	v_cvt_pk_bf16_f32 v235, v86, v87
	v_cvt_pk_bf16_f32 v236, v80, v81
	v_cvt_pk_bf16_f32 v237, v82, v83
	v_add_co_u32_e32 v246, vcc, 0x10100, v244
	v_addc_co_u32_e32 v247, vcc, 0, v245, vcc
	v_permlane16_swap_b32 v234, v236
	v_permlane16_swap_b32 v235, v237
	global_store_dwordx4 v[246:247], v[234:237], off
	v_cvt_pk_bf16_f32 v230, v76, v77
	v_cvt_pk_bf16_f32 v231, v78, v79
	v_cvt_pk_bf16_f32 v232, v72, v73
	v_cvt_pk_bf16_f32 v233, v74, v75
	v_add_co_u32_e32 v246, vcc, 0x18000, v244
	v_addc_co_u32_e32 v247, vcc, 0, v245, vcc
	v_permlane16_swap_b32 v230, v232
	v_permlane16_swap_b32 v231, v233
	global_store_dwordx4 v[246:247], v[230:233], off
	v_cvt_pk_bf16_f32 v234, v68, v69
	v_cvt_pk_bf16_f32 v235, v70, v71
	v_cvt_pk_bf16_f32 v236, v64, v65
	v_cvt_pk_bf16_f32 v237, v66, v67
	v_add_co_u32_e32 v246, vcc, 0x18100, v244
	v_addc_co_u32_e32 v247, vcc, 0, v245, vcc
	v_permlane16_swap_b32 v234, v236
	v_permlane16_swap_b32 v235, v237
	global_store_dwordx4 v[246:247], v[234:237], off
	v_cvt_pk_bf16_f32 v230, v60, v61
	v_cvt_pk_bf16_f32 v231, v62, v63
	v_cvt_pk_bf16_f32 v232, v56, v57
	v_cvt_pk_bf16_f32 v233, v58, v59
	v_add_co_u32_e32 v246, vcc, 0x40000, v244
	v_addc_co_u32_e32 v247, vcc, 0, v245, vcc
	v_permlane16_swap_b32 v230, v232
	v_permlane16_swap_b32 v231, v233
	global_store_dwordx4 v[246:247], v[230:233], off
	v_cvt_pk_bf16_f32 v234, v52, v53
	v_cvt_pk_bf16_f32 v235, v54, v55
	v_cvt_pk_bf16_f32 v236, v48, v49
	v_cvt_pk_bf16_f32 v237, v50, v51
	v_add_co_u32_e32 v246, vcc, 0x40100, v244
	v_addc_co_u32_e32 v247, vcc, 0, v245, vcc
	v_permlane16_swap_b32 v234, v236
	v_permlane16_swap_b32 v235, v237
	global_store_dwordx4 v[246:247], v[234:237], off
	v_cvt_pk_bf16_f32 v230, v44, v45
	v_cvt_pk_bf16_f32 v231, v46, v47
	v_cvt_pk_bf16_f32 v232, v40, v41
	v_cvt_pk_bf16_f32 v233, v42, v43
	v_add_co_u32_e32 v246, vcc, 0x48000, v244
	v_addc_co_u32_e32 v247, vcc, 0, v245, vcc
	v_permlane16_swap_b32 v230, v232
	v_permlane16_swap_b32 v231, v233
	global_store_dwordx4 v[246:247], v[230:233], off
	v_cvt_pk_bf16_f32 v234, v36, v37
	v_cvt_pk_bf16_f32 v235, v38, v39
	v_cvt_pk_bf16_f32 v236, v32, v33
	v_cvt_pk_bf16_f32 v237, v34, v35
	v_add_co_u32_e32 v246, vcc, 0x48100, v244
	v_addc_co_u32_e32 v247, vcc, 0, v245, vcc
	v_permlane16_swap_b32 v234, v236
	v_permlane16_swap_b32 v235, v237
	global_store_dwordx4 v[246:247], v[234:237], off
	v_cvt_pk_bf16_f32 v230, v28, v29
	v_cvt_pk_bf16_f32 v231, v30, v31
	v_cvt_pk_bf16_f32 v232, v24, v25
	v_cvt_pk_bf16_f32 v233, v26, v27
	v_add_co_u32_e32 v246, vcc, 0x50000, v244
	v_addc_co_u32_e32 v247, vcc, 0, v245, vcc
	v_permlane16_swap_b32 v230, v232
	v_permlane16_swap_b32 v231, v233
	global_store_dwordx4 v[246:247], v[230:233], off
	v_cvt_pk_bf16_f32 v234, v20, v21
	v_cvt_pk_bf16_f32 v235, v22, v23
	v_cvt_pk_bf16_f32 v236, v16, v17
	v_cvt_pk_bf16_f32 v237, v18, v19
	v_add_co_u32_e32 v246, vcc, 0x50100, v244
	v_addc_co_u32_e32 v247, vcc, 0, v245, vcc
	v_permlane16_swap_b32 v234, v236
	v_permlane16_swap_b32 v235, v237
	global_store_dwordx4 v[246:247], v[234:237], off
	v_cvt_pk_bf16_f32 v230, v12, v13
	v_cvt_pk_bf16_f32 v231, v14, v15
	v_cvt_pk_bf16_f32 v232, v8, v9
	v_cvt_pk_bf16_f32 v233, v10, v11
	v_add_co_u32_e32 v246, vcc, 0x58000, v244
	v_addc_co_u32_e32 v247, vcc, 0, v245, vcc
	v_permlane16_swap_b32 v230, v232
	v_permlane16_swap_b32 v231, v233
	global_store_dwordx4 v[246:247], v[230:233], off
	v_cvt_pk_bf16_f32 v234, v4, v5
	v_cvt_pk_bf16_f32 v235, v6, v7
	v_cvt_pk_bf16_f32 v236, v0, v1
	v_cvt_pk_bf16_f32 v237, v2, v3
	v_add_co_u32_e32 v246, vcc, 0x58100, v244
	v_addc_co_u32_e32 v247, vcc, 0, v245, vcc
	v_permlane16_swap_b32 v234, v236
	v_permlane16_swap_b32 v235, v237
	global_store_dwordx4 v[246:247], v[234:237], off
	s_branch .LBB0_1065
